# grid barrier: acquire-side buffer_inv issued at arrival (overlaps the arrive atomic and the wait for the release) instead of after the release flag is seen
# speedup vs baseline: 1.0282x; 1.0162x over previous
; __device__ __forceinline__ unsigned xb_ld(unsigned* p)              { return __hip_atomic_load(p, __ATOMIC_RELAXED, __HIP_MEMORY_SCOPE_AGENT); }
; __device__ __forceinline__ unsigned xb_add(unsigned* p, unsigned v) { return __hip_atomic_fetch_add(p, v, __ATOMIC_RELAXED, __HIP_MEMORY_SCOPE_AGENT); }
; #define XB_SPIN(cond, bar) do { unsigned _sp = 0; while (cond) { __builtin_amdgcn_s_sleep(1); \
;     if ((++_sp & 255u) == 0u) { if (xb_ld(&(bar)[XB_TMO])) break; if (_sp > XB_SPIN_CAP) { atomicAdd(&(bar)[XB_TMO], 1u); break; } } } } while (0)
; __device__ __forceinline__ void xcd_barrier(const XcdBarrier& b, const int tid) {
;     ...
;         const unsigned old = xb_add(&bar[XB_XSUB(b.x)], 1u);
;         const unsigned gen = old / nloc;
;         if (old + 1u == (gen + 1u) * nloc) {
;             __builtin_amdgcn_fence(__ATOMIC_RELEASE, "agent");
;             asm volatile("s_waitcnt vmcnt(0)" ::: "memory");
;             const unsigned og = xb_add(&bar[XB_TOP], 1u);
;             const unsigned tg = og / nx;
;             if (og + 1u == (tg + 1u) * nx) xb_add(&bar[XB_TOPGEN], 1u);
;             else XB_SPIN(xb_ld(&bar[XB_TOPGEN]) == tg, bar);
;             __builtin_amdgcn_fence(__ATOMIC_ACQUIRE, "agent");
;             xb_add(&bar[XB_XGEN(b.x)], 1u);
;             asm volatile("s_waitcnt vmcnt(0)" ::: "memory");
;         } else {
;             XB_SPIN(xb_ld(&bar[XB_XGEN(b.x)]) == gen, bar);
.LBB0_40:
	s_or_b64 exec, exec, s[6:7]
	buffer_inv sc1
	v_cvt_f32_u32_e32 v5, v3
	s_waitcnt vmcnt(0)
	v_readfirstlane_b32 s4, v4
	v_sub_u32_e32 v4, 0, v3
	v_rcp_iflag_f32_e32 v5, v5
	v_add_u32_e32 v6, s4, v1
	v_mul_f32_e32 v5, 0x4f7ffffe, v5
	v_cvt_u32_f32_e32 v5, v5
	v_mul_lo_u32 v1, v4, v5
	v_mul_hi_u32 v1, v5, v1
	v_add_u32_e32 v1, v5, v1
	v_mul_hi_u32 v1, v6, v1
	v_mul_lo_u32 v4, v1, v3
	v_sub_u32_e32 v4, v6, v4
	v_add_u32_e32 v5, 1, v1
	v_cmp_ge_u32_e32 vcc, v4, v3
	s_nop 1
	v_cndmask_b32_e32 v1, v1, v5, vcc
	v_sub_u32_e32 v5, v4, v3
	v_cndmask_b32_e32 v4, v4, v5, vcc
	v_add_u32_e32 v5, 1, v1
	v_cmp_ge_u32_e32 vcc, v4, v3
	v_add_u32_e32 v4, 1, v6
	s_nop 0
	v_cndmask_b32_e32 v1, v1, v5, vcc
	v_mul_lo_u32 v5, v3, v1
	v_add_u32_e32 v3, v5, v3
	v_cmp_ne_u32_e32 vcc, v4, v3
	s_and_saveexec_b64 s[4:5], vcc
	s_xor_b64 s[4:5], exec, s[4:5]
	s_cbranch_execz .LBB0_54
	s_waitcnt lgkmcnt(0)
	s_add_u32 s10, s22, 0x11d03500
	s_addc_u32 s11, s23, 0
	global_load_dword v2, v179, s[10:11] sc1
	s_nop 0
	s_waitcnt vmcnt(0)
	v_cmp_eq_u32_e32 vcc, v2, v1
	s_and_saveexec_b64 s[6:7], vcc
	s_cbranch_execz .LBB0_53
	s_add_u32 s8, s22, 0x11d00200
	s_addc_u32 s9, s23, 0
	s_mov_b32 s24, 1
	s_mov_b64 s[12:13], 0
	s_branch .LBB0_44

; __device__ __forceinline__ unsigned xb_ld(unsigned* p)              { return __hip_atomic_load(p, __ATOMIC_RELAXED, __HIP_MEMORY_SCOPE_AGENT); }
; #define XB_SPIN(cond, bar) do { unsigned _sp = 0; while (cond) { __builtin_amdgcn_s_sleep(1); \
;     if ((++_sp & 255u) == 0u) { if (xb_ld(&(bar)[XB_TMO])) break; if (_sp > XB_SPIN_CAP) { atomicAdd(&(bar)[XB_TMO], 1u); break; } } } } while (0)
; __device__ __forceinline__ void xcd_barrier(const XcdBarrier& b, const int tid) {
;     ...
;             XB_SPIN(xb_ld(&bar[XB_XGEN(b.x)]) == gen, bar);
;             __builtin_amdgcn_fence(__ATOMIC_ACQUIRE, "agent");
;             asm volatile("s_waitcnt vmcnt(0)" ::: "memory");
.LBB0_53:
	s_or_b64 exec, exec, s[6:7]
	s_waitcnt vmcnt(0)
	s_nop 0
	s_waitcnt vmcnt(0)

; __device__ __forceinline__ unsigned xb_add(unsigned* p, unsigned v) { return __hip_atomic_fetch_add(p, v, __ATOMIC_RELAXED, __HIP_MEMORY_SCOPE_AGENT); }
; __device__ __forceinline__ void xcd_barrier(const XcdBarrier& b, const int tid) {
;     ...
;             __builtin_amdgcn_fence(__ATOMIC_ACQUIRE, "agent");
;             xb_add(&bar[XB_XGEN(b.x)], 1u);
.LBB0_71:
	s_or_b64 exec, exec, s[4:5]
	s_mov_b64 s[4:5], exec
	v_mbcnt_lo_u32_b32 v1, s4, 0
	v_mbcnt_hi_u32_b32 v1, s5, v1
	v_cmp_eq_u32_e32 vcc, 0, v1
	s_waitcnt vmcnt(0)
	s_nop 0
	s_and_saveexec_b64 s[6:7], vcc
	s_cbranch_execz .LBB0_73
	s_bcnt1_i32_b64 s4, s[4:5]
	v_mov_b32_e32 v1, s4
	v_mov_b32_e32 v2, 0x2000
